# P3 RWKV: compute waves store y through 32-bit lane offsets + scalar chunk base with paired bf16 converts (d16_hi stores); loader waves keep constant lane offsets and advance two scalar bases instead o
# speedup vs baseline: 1.0038x; 1.0038x over previous
; template <bool RWKV> __device__ __forceinline__ void scan_chunk(const LAS unsigned char* buf, const LAS unsigned char* img, f32x16 (&T)[2], const ScanSrc& S, int chunk, int w, int lane) {
;     ...
;         const int s0 = chunk * SC_CH; const long tok0 = (long)S.tokbase + (S.rev ? T_SEQ - 1 - s0 : s0), dstep = S.rev ? -512 : 512;
;         bf16_t* op = S.out + tok0 * 512 + 32 * w + r;
; template <bool RWKV> __device__ __forceinline__ void scan_item(LAS unsigned char* lds, const ScanSrc& S, int wid, int lane) {
;     ...
;     const bool is_ld = (wid == 4) | (wid == 5) | (wid == 3) | (wid == 7); const bool is_prep = wid == 2;
;     const int lt = (wid == 4 ? 0 : wid == 5 ? 64 : wid == 3 ? 128 : 192) + lane;
;     ScanLd L;
;     constexpr int NCH = T_SEQ / SC_CH;
;     ...
;     const bool is_inv = wid == 6;
;     if (is_ld) { scan_load_issue<RWKV>(L, S, 0, lt); scan_load_finish<RWKV>(lds, L, lt); scan_load_issue<RWKV>(L, S, 1, lt); scan_load_finish<RWKV>(lds + SC_BUF, L, lt);
;                  scan_load_issue<RWKV>(L, S, 2, lt); scan_load_finish<RWKV>(lds + 2 * SC_BUF, L, lt); scan_load_issue<RWKV>(L, S, 3, lt); }
.LBB0_611:
	s_or_b64 exec, exec, s[72:73]
	s_lshl_b32 s72, s89, 25
	s_add_u32 s72, s56, s72
	s_addc_u32 s73, s57, 0
	s_add_u32 s72, s72, s93
	v_lshlrev_b32_e32 v74, 1, v20
	s_addc_u32 s73, s73, 0
	s_lshr_b32 s89, s81, 2
	v_lshl_add_u64 v[88:89], s[0:1], 0, v[74:75]
	s_lshl_b64 s[0:1], s[86:87], 1
	v_or_b32_e32 v0, s89, v122
	s_add_u32 s0, s72, s0
	v_lshlrev_b32_e32 v182, 1, v0
	v_mul_u32_u24_e32 v183, 0x50, v0
	v_mul_u32_u24_e32 v184, 48, v0
	v_mad_u32_u24 v185, v0, s88, s88
	v_mad_u32_u24 v186, v0, s88, v180
	v_mad_u32_u24 v187, v0, s88, v181
	v_lshlrev_b32_e32 v188, 2, v0
	v_lshl_add_u64 v[90:91], s[60:61], 0, v[74:75]
	v_lshl_add_u64 v[92:93], s[68:69], 0, v[74:75]
	v_lshl_add_u64 v[94:95], s[70:71], 0, v[74:75]
	v_lshl_add_u64 v[96:97], s[42:43], 0, v[74:75]
	v_lshl_add_u64 v[98:99], s[66:67], 0, v[74:75]
	s_addc_u32 s1, s73, s1
	v_lshlrev_b32_e32 v74, 1, v72
	s_ashr_i32 s66, s83, 31
	v_add_u32_e32 v0, s81, v73
	s_waitcnt lgkmcnt(0)
	s_barrier
	v_lshl_add_u64 v[100:101], s[0:1], 0, v[74:75]
	s_and_b64 s[0:1], s[40:41], exec
	s_movk_i32 s89, 0x200
	v_bfe_u32 v0, v0, 2, 4
	s_cselect_b32 s0, s89, 0xfffffe00
	v_or_b32_e32 v74, 64, v0
	v_sub_u32_e32 v189, 0, v0
	v_mov_b32_e32 v0, 0
	v_mul_hi_i32_i24_e32 v103, s0, v138
	v_mul_i32_i24_e32 v102, s0, v138
	v_mul_hi_i32_i24_e32 v105, s0, v139
	v_mul_i32_i24_e32 v104, s0, v139
	v_mul_hi_i32_i24_e32 v107, s0, v140
	v_mul_i32_i24_e32 v106, s0, v140
	v_mul_hi_i32_i24_e32 v109, s0, v141
	v_mul_i32_i24_e32 v108, s0, v141
	v_mul_hi_i32_i24_e32 v111, s0, v142
	v_mul_i32_i24_e32 v110, s0, v142
	v_mul_hi_i32_i24_e32 v113, s0, v143
	v_mul_i32_i24_e32 v112, s0, v143
	v_mul_hi_i32_i24_e32 v115, s0, v144
	v_mul_i32_i24_e32 v114, s0, v144
	v_mul_hi_i32_i24_e32 v117, s0, v145
	v_mul_i32_i24_e32 v116, s0, v145
	s_mov_b32 s67, 0
	s_movk_i32 s68, 0xfbf
	s_mov_b32 s69, 0
	s_mov_b32 s72, 0
	s_mov_b32 s70, 0
	v_mov_b32_e32 v1, v0
	v_mov_b32_e32 v2, v0
	v_mov_b32_e32 v3, v0
	v_mov_b32_e32 v4, v0
	v_mov_b32_e32 v5, v0
	v_mov_b32_e32 v6, v0
	v_mov_b32_e32 v7, v0
	v_mov_b32_e32 v8, v0
	v_mov_b32_e32 v9, v0
	v_mov_b32_e32 v10, v0
	v_mov_b32_e32 v11, v0
	v_mov_b32_e32 v12, v0
	v_mov_b32_e32 v13, v0
	v_mov_b32_e32 v14, v0
	v_mov_b32_e32 v15, v0
	v_mov_b32_e32 v16, v0
	v_mov_b32_e32 v17, v0
	v_mov_b32_e32 v18, v0
	v_mov_b32_e32 v19, v0
	v_mov_b32_e32 v20, v0
	v_mov_b32_e32 v21, v0
	v_mov_b32_e32 v22, v0
	v_mov_b32_e32 v23, v0
	v_mov_b32_e32 v24, v0
	v_mov_b32_e32 v25, v0
	v_mov_b32_e32 v26, v0
	v_mov_b32_e32 v27, v0
	v_mov_b32_e32 v28, v0
	v_mov_b32_e32 v29, v0
	v_mov_b32_e32 v30, v0
	v_mov_b32_e32 v31, v0
	v_and_b32_e32 v251, 3, v73
	v_and_b32_e32 v252, 48, v73
	v_add_u32_e32 v251, v251, v252
	v_add_u32_e32 v251, -4, v251
	v_and_b32_e32 v253, 16, v73
	v_cmp_ne_u32_e32 vcc, 0, v253
	v_and_b32_e32 v252, 3, v73
	v_add_u32_e32 v252, 28, v252
	v_cndmask_b32_e32 v251, v73, v251, vcc
	v_cndmask_b32_e64 v253, 0, 1.0, vcc
	v_cmp_lt_u32_e32 vcc, 31, v73
	v_lshlrev_b32_e32 v251, 2, v251
	v_lshlrev_b32_e32 v252, 2, v252
	v_cndmask_b32_e64 v245, 0, 1.0, vcc
	v_add_u32_e32 v248, v123, v182
	v_add_u32_e32 v249, v183, v127
	v_add_u32_e32 v250, v184, v127
	v_add_u32_e32 v33, 0xfbf, v189
	v_cndmask_b32_e64 v32, v33, v74, s[40:41]
	v_add_u32_e32 v32, s83, v32
	v_ashrrev_i32_e32 v33, 31, v32
	v_lshlrev_b64 v[34:35], 10, v[32:33]
	v_lshl_add_u64 v[234:235], v[88:89], 0, v[34:35]
	v_mad_i64_i32 v[236:237], s[0:1], v32, s79, v[90:91]
	v_mad_i64_i32 v[238:239], s[0:1], v32, s79, v[92:93]
	v_mad_i64_i32 v[240:241], s[0:1], v32, s79, v[94:95]
	v_lshl_add_u64 v[242:243], v[96:97], 0, v[34:35]
	v_lshl_add_u64 v[246:247], v[98:99], 0, v[34:35]
	s_cmp_lt_i32 s3, 2
	s_cbranch_scc0 .Lrw_init_noty
	v_readfirstlane_b32 s98, v100
	v_readfirstlane_b32 s99, v101
	s_nop 3
	v_subrev_u32_e32 v32, s98, v100
	v_add_u32_e32 v32, 0x8000, v32
	v_lshl_add_u32 v102, v102, 1, v32
	v_lshl_add_u32 v104, v104, 1, v32
	v_lshl_add_u32 v106, v106, 1, v32
	v_lshl_add_u32 v108, v108, 1, v32
	v_lshl_add_u32 v110, v110, 1, v32
	v_lshl_add_u32 v112, v112, 1, v32
	v_lshl_add_u32 v114, v114, 1, v32
	v_lshl_add_u32 v116, v116, 1, v32
	s_sub_u32 s98, s98, 0x8000
	s_subb_u32 s99, s99, 0
	s_branch .Lrw_init_done
.Lrw_init_noty:
	s_cmp_lt_i32 s3, 3
	s_cbranch_scc1 .Lrw_init_done
	s_cmp_eq_u32 s3, 6
	s_cbranch_scc1 .Lrw_init_done
	v_subrev_u32_e32 v234, s58, v234
	v_subrev_u32_e32 v236, s58, v236
	v_subrev_u32_e32 v238, s58, v238
	v_subrev_u32_e32 v240, s58, v240
	v_subrev_u32_e32 v242, s58, v242
	v_subrev_u32_e32 v246, s58, v246
	s_mov_b64 s[98:99], s[58:59]
	s_mov_b64 s[100:101], s[58:59]
	global_load_dwordx2 v[222:223], v234, s[98:99]
	global_load_dwordx2 v[224:225], v236, s[100:101]
	global_load_dwordx2 v[226:227], v238, s[100:101]
	global_load_dwordx2 v[228:229], v240, s[100:101]
	global_load_dwordx2 v[230:231], v242, s[98:99]
	global_load_dwordx2 v[232:233], v246, s[98:99]
	s_and_b64 s[42:43], s[40:41], exec
	s_mov_b32 s1, 0x4000
	s_cselect_b32 s1, s1, 0xffffc000
	s_mov_b32 s42, 0xc000
	s_cselect_b32 s42, s42, 0xffff4000
	s_cselect_b32 s43, 0, -1
	s_add_u32 s98, s98, s1
	s_addc_u32 s99, s99, s43
	s_add_u32 s100, s100, s42
	s_addc_u32 s101, s101, s43

; __device__ __forceinline__ void unpack4(const u32x2 w, float (&f)[4]) { f[0] = bflo(w.x); f[1] = bfhi(w.x); f[2] = bflo(w.y); f[3] = bfhi(w.y); }
; template <bool RWKV> __device__ __forceinline__ void scan_load_finish(LAS unsigned char* buf, const ScanLd& L, int lt) {
;     const int lw = lt >> 6, lane = lt & 63, sl = lane >> 2, col = 16 * lw + 4 * (lane & 3);
;     float d[4], c[4], k[4], r[4], v[4], kk[4], nb[4];
;     unpack4(L.rd, d); unpack4(L.rk, k); unpack4(L.rr, r); unpack4(L.rv, v); unpack4(L.rkk, kk); unpack4(L.rnb, nb);
; #pragma unroll
;     for (int i = 0; i < 4; ++i) c[i] = d[i];
; #pragma unroll
;     for (int dl = 4; dl < 64; dl <<= 1)
; #pragma unroll
;         for (int i = 0; i < 4; ++i) { const float t = __shfl_up(c[i], dl); c[i] += (lane >= dl) ? t : 0.f; }
;     float o1[4], o2[4], o3[4], o4[4]; f32x4 we;
; #pragma unroll
;     for (int i = 0; i < 4; ++i) { const float W = __expf(-c[i]), iW = __expf(c[i]), Wp = __expf(d[i] - c[i]); o1[i] = RWKV ? kk[i] * Wp : 0.f; o2[i] = RWKV ? nb[i] * iW : 0.f; o3[i] = k[i] * iW; o4[i] = r[i] * W; we[i] = W; }
;     u32x2 w;
;     w.x = cvt2(o1[0], o1[1]); w.y = cvt2(o1[2], o1[3]); *(LAS u32x2*)(buf + SB_XA + sl * 144 + col * 2) = w;
;     w.x = cvt2(o4[0], o4[1]); w.y = cvt2(o4[2], o4[3]); *(LAS u32x2*)(buf + SB_XA + (16 + sl) * 144 + col * 2) = w;
;     w.x = cvt2(o2[0], o2[1]); w.y = cvt2(o2[2], o2[3]); *(LAS u32x2*)(buf + SB_XB + sl * 144 + col * 2) = w;
;     w.x = cvt2(o3[0], o3[1]); w.y = cvt2(o3[2], o3[3]); *(LAS u32x2*)(buf + SB_XB + (16 + sl) * 144 + col * 2) = w;
; #pragma unroll
;     for (int i = 0; i < 4; ++i) {
;         *(LAS unsigned short*)(buf + SB_XBT + (col + i) * 80 + sl * 2) = (unsigned short)(cvt2(o2[i], 0.f) & 0xffffu);
;         *(LAS unsigned short*)(buf + SB_XBT + (col + i) * 80 + (16 + sl) * 2) = (unsigned short)(cvt2(o3[i], 0.f) & 0xffffu);
;         *(LAS unsigned short*)(buf + SB_VT + (col + i) * 48 + sl * 2) = (unsigned short)(cvt2(v[i], 0.f) & 0xffffu); }
; template <bool RWKV> __device__ __forceinline__ void scan_item(LAS unsigned char* lds, const ScanSrc& S, int wid, int lane) {
;     ...
;             if (c + 3 < NCH) scan_load_finish<RWKV>(lds + ((b0 + 3) & 3) * SC_BUF, L, lt);
;             if (c + 4 < NCH) scan_load_issue<RWKV>(L, S, c + 4, lt); }
.LBB0_640:
	s_cmpk_gt_u32 s69, 0xfc
	s_cbranch_scc1 .LBB0_613
	s_add_i32 s0, s70, -1
	s_and_b32 s0, s0, 3
	s_mulk_i32 s0, 0x4500
	v_add_u32_e32 v190, s0, v250
	s_bitcmp1_b32 s69, 0
	s_cbranch_scc1 .Lrw_ld_odd
	s_cmpk_gt_u32 s69, 0xfa
	s_cbranch_scc1 .Lrw_ld_e_tail
	s_waitcnt vmcnt(6)
	v_lshlrev_b32_e32 v32, 16, v76
	v_and_b32_e32 v33, 0xffff0000, v76
	v_lshlrev_b32_e32 v34, 16, v77
	v_and_b32_e32 v35, 0xffff0000, v77
	v_mul_f32_e32 v52, 0x3fb8aa3b, v32
	v_mul_f32_e32 v53, 0x3fb8aa3b, v33
	v_mul_f32_e32 v54, 0x3fb8aa3b, v34
	v_mul_f32_e32 v55, 0x3fb8aa3b, v35
	v_add_f32_dpp v52, v52, v52 row_shr:4 row_mask:0xf bank_mask:0xf
	v_add_f32_dpp v53, v53, v53 row_shr:4 row_mask:0xf bank_mask:0xf
	v_add_f32_dpp v54, v54, v54 row_shr:4 row_mask:0xf bank_mask:0xf
	v_add_f32_dpp v55, v55, v55 row_shr:4 row_mask:0xf bank_mask:0xf
	v_add_f32_dpp v52, v52, v52 row_shr:8 row_mask:0xf bank_mask:0xf
	v_add_f32_dpp v53, v53, v53 row_shr:8 row_mask:0xf bank_mask:0xf
	v_add_f32_dpp v54, v54, v54 row_shr:8 row_mask:0xf bank_mask:0xf
	v_add_f32_dpp v55, v55, v55 row_shr:8 row_mask:0xf bank_mask:0xf
	ds_bpermute_b32 v60, v251, v52
	ds_bpermute_b32 v61, v251, v53
	ds_bpermute_b32 v62, v251, v54
	ds_bpermute_b32 v63, v251, v55
	ds_write_b16 v190, v82 offset:14336
	ds_write_b16_d16_hi v190, v82 offset:14384
	ds_write_b16 v190, v83 offset:14432
	ds_write_b16_d16_hi v190, v83 offset:14480
	v_lshlrev_b32_e32 v36, 16, v78
	v_and_b32_e32 v37, 0xffff0000, v78
	v_lshlrev_b32_e32 v38, 16, v79
	v_and_b32_e32 v39, 0xffff0000, v79
	v_lshlrev_b32_e32 v40, 16, v80
	v_and_b32_e32 v41, 0xffff0000, v80
	v_lshlrev_b32_e32 v42, 16, v81
	v_and_b32_e32 v43, 0xffff0000, v81
	v_lshlrev_b32_e32 v44, 16, v84
	v_and_b32_e32 v45, 0xffff0000, v84
	v_lshlrev_b32_e32 v46, 16, v85
	v_and_b32_e32 v47, 0xffff0000, v85
	v_lshlrev_b32_e32 v48, 16, v86
	v_and_b32_e32 v49, 0xffff0000, v86
	v_lshlrev_b32_e32 v50, 16, v87
	v_and_b32_e32 v51, 0xffff0000, v87
	s_waitcnt lgkmcnt(4)
	v_fmac_f32_e32 v52, v60, v253
	v_fmac_f32_e32 v53, v61, v253
	v_fmac_f32_e32 v54, v62, v253
	v_fmac_f32_e32 v55, v63, v253
	ds_bpermute_b32 v60, v252, v52
	ds_bpermute_b32 v61, v252, v53
	ds_bpermute_b32 v62, v252, v54
	ds_bpermute_b32 v63, v252, v55
	global_load_dwordx2 v[76:77], v234, s[98:99]
	global_load_dwordx2 v[78:79], v236, s[100:101]
	global_load_dwordx2 v[80:81], v238, s[100:101]
	global_load_dwordx2 v[82:83], v240, s[100:101]
	global_load_dwordx2 v[84:85], v242, s[98:99]
	global_load_dwordx2 v[86:87], v246, s[98:99]
	s_and_b64 s[42:43], s[40:41], exec
	s_mov_b32 s1, 0x4000
	s_cselect_b32 s1, s1, 0xffffc000
	s_mov_b32 s42, 0xc000
	s_cselect_b32 s42, s42, 0xffff4000
	s_cselect_b32 s43, 0, -1
	s_add_u32 s98, s98, s1
	s_addc_u32 s99, s99, s43
	s_add_u32 s100, s100, s42
	s_addc_u32 s101, s101, s43
	s_waitcnt lgkmcnt(0)
	v_fmac_f32_e32 v52, v60, v245
	v_fmac_f32_e32 v53, v61, v245
	v_fmac_f32_e32 v54, v62, v245
	v_fmac_f32_e32 v55, v63, v245
	s_branch .Lrw_ldfin

; __device__ __forceinline__ void unpack4(const u32x2 w, float (&f)[4]) { f[0] = bflo(w.x); f[1] = bfhi(w.x); f[2] = bflo(w.y); f[3] = bfhi(w.y); }
; template <bool RWKV> __device__ __forceinline__ void scan_load_finish(LAS unsigned char* buf, const ScanLd& L, int lt) {
;     const int lw = lt >> 6, lane = lt & 63, sl = lane >> 2, col = 16 * lw + 4 * (lane & 3);
;     float d[4], c[4], k[4], r[4], v[4], kk[4], nb[4];
;     unpack4(L.rd, d); unpack4(L.rk, k); unpack4(L.rr, r); unpack4(L.rv, v); unpack4(L.rkk, kk); unpack4(L.rnb, nb);
; #pragma unroll
;     for (int i = 0; i < 4; ++i) c[i] = d[i];
; #pragma unroll
;     for (int dl = 4; dl < 64; dl <<= 1)
; #pragma unroll
;         for (int i = 0; i < 4; ++i) { const float t = __shfl_up(c[i], dl); c[i] += (lane >= dl) ? t : 0.f; }
;     float o1[4], o2[4], o3[4], o4[4]; f32x4 we;
; #pragma unroll
;     for (int i = 0; i < 4; ++i) { const float W = __expf(-c[i]), iW = __expf(c[i]), Wp = __expf(d[i] - c[i]); o1[i] = RWKV ? kk[i] * Wp : 0.f; o2[i] = RWKV ? nb[i] * iW : 0.f; o3[i] = k[i] * iW; o4[i] = r[i] * W; we[i] = W; }
;     u32x2 w;
;     w.x = cvt2(o1[0], o1[1]); w.y = cvt2(o1[2], o1[3]); *(LAS u32x2*)(buf + SB_XA + sl * 144 + col * 2) = w;
;     w.x = cvt2(o4[0], o4[1]); w.y = cvt2(o4[2], o4[3]); *(LAS u32x2*)(buf + SB_XA + (16 + sl) * 144 + col * 2) = w;
;     w.x = cvt2(o2[0], o2[1]); w.y = cvt2(o2[2], o2[3]); *(LAS u32x2*)(buf + SB_XB + sl * 144 + col * 2) = w;
;     w.x = cvt2(o3[0], o3[1]); w.y = cvt2(o3[2], o3[3]); *(LAS u32x2*)(buf + SB_XB + (16 + sl) * 144 + col * 2) = w;
; #pragma unroll
;     for (int i = 0; i < 4; ++i) {
;         *(LAS unsigned short*)(buf + SB_XBT + (col + i) * 80 + sl * 2) = (unsigned short)(cvt2(o2[i], 0.f) & 0xffffu);
;         *(LAS unsigned short*)(buf + SB_XBT + (col + i) * 80 + (16 + sl) * 2) = (unsigned short)(cvt2(o3[i], 0.f) & 0xffffu);
;         *(LAS unsigned short*)(buf + SB_VT + (col + i) * 48 + sl * 2) = (unsigned short)(cvt2(v[i], 0.f) & 0xffffu); }
; template <bool RWKV> __device__ __forceinline__ void scan_item(LAS unsigned char* lds, const ScanSrc& S, int wid, int lane) {
;     ...
;             if (c + 3 < NCH) scan_load_finish<RWKV>(lds + ((b0 + 3) & 3) * SC_BUF, L, lt);
;             if (c + 4 < NCH) scan_load_issue<RWKV>(L, S, c + 4, lt); }
.Lrw_ld_odd:
	s_cmpk_gt_u32 s69, 0xfa
	s_cbranch_scc1 .Lrw_ld_o_tail
	s_waitcnt vmcnt(6)
	v_lshlrev_b32_e32 v32, 16, v222
	v_and_b32_e32 v33, 0xffff0000, v222
	v_lshlrev_b32_e32 v34, 16, v223
	v_and_b32_e32 v35, 0xffff0000, v223
	v_mul_f32_e32 v52, 0x3fb8aa3b, v32
	v_mul_f32_e32 v53, 0x3fb8aa3b, v33
	v_mul_f32_e32 v54, 0x3fb8aa3b, v34
	v_mul_f32_e32 v55, 0x3fb8aa3b, v35
	v_add_f32_dpp v52, v52, v52 row_shr:4 row_mask:0xf bank_mask:0xf
	v_add_f32_dpp v53, v53, v53 row_shr:4 row_mask:0xf bank_mask:0xf
	v_add_f32_dpp v54, v54, v54 row_shr:4 row_mask:0xf bank_mask:0xf
	v_add_f32_dpp v55, v55, v55 row_shr:4 row_mask:0xf bank_mask:0xf
	v_add_f32_dpp v52, v52, v52 row_shr:8 row_mask:0xf bank_mask:0xf
	v_add_f32_dpp v53, v53, v53 row_shr:8 row_mask:0xf bank_mask:0xf
	v_add_f32_dpp v54, v54, v54 row_shr:8 row_mask:0xf bank_mask:0xf
	v_add_f32_dpp v55, v55, v55 row_shr:8 row_mask:0xf bank_mask:0xf
	ds_bpermute_b32 v60, v251, v52
	ds_bpermute_b32 v61, v251, v53
	ds_bpermute_b32 v62, v251, v54
	ds_bpermute_b32 v63, v251, v55
	ds_write_b16 v190, v228 offset:14336
	ds_write_b16_d16_hi v190, v228 offset:14384
	ds_write_b16 v190, v229 offset:14432
	ds_write_b16_d16_hi v190, v229 offset:14480
	v_lshlrev_b32_e32 v36, 16, v224
	v_and_b32_e32 v37, 0xffff0000, v224
	v_lshlrev_b32_e32 v38, 16, v225
	v_and_b32_e32 v39, 0xffff0000, v225
	v_lshlrev_b32_e32 v40, 16, v226
	v_and_b32_e32 v41, 0xffff0000, v226
	v_lshlrev_b32_e32 v42, 16, v227
	v_and_b32_e32 v43, 0xffff0000, v227
	v_lshlrev_b32_e32 v44, 16, v230
	v_and_b32_e32 v45, 0xffff0000, v230
	v_lshlrev_b32_e32 v46, 16, v231
	v_and_b32_e32 v47, 0xffff0000, v231
	v_lshlrev_b32_e32 v48, 16, v232
	v_and_b32_e32 v49, 0xffff0000, v232
	v_lshlrev_b32_e32 v50, 16, v233
	v_and_b32_e32 v51, 0xffff0000, v233
	s_waitcnt lgkmcnt(4)
	v_fmac_f32_e32 v52, v60, v253
	v_fmac_f32_e32 v53, v61, v253
	v_fmac_f32_e32 v54, v62, v253
	v_fmac_f32_e32 v55, v63, v253
	ds_bpermute_b32 v60, v252, v52
	ds_bpermute_b32 v61, v252, v53
	ds_bpermute_b32 v62, v252, v54
	ds_bpermute_b32 v63, v252, v55
	global_load_dwordx2 v[222:223], v234, s[98:99]
	global_load_dwordx2 v[224:225], v236, s[100:101]
	global_load_dwordx2 v[226:227], v238, s[100:101]
	global_load_dwordx2 v[228:229], v240, s[100:101]
	global_load_dwordx2 v[230:231], v242, s[98:99]
	global_load_dwordx2 v[232:233], v246, s[98:99]
	s_and_b64 s[42:43], s[40:41], exec
	s_mov_b32 s1, 0x4000
	s_cselect_b32 s1, s1, 0xffffc000
	s_mov_b32 s42, 0xc000
	s_cselect_b32 s42, s42, 0xffff4000
	s_cselect_b32 s43, 0, -1
	s_add_u32 s98, s98, s1
	s_addc_u32 s99, s99, s43
	s_add_u32 s100, s100, s42
	s_addc_u32 s101, s101, s43
	s_waitcnt lgkmcnt(0)
	v_fmac_f32_e32 v52, v60, v245
	v_fmac_f32_e32 v53, v61, v245
	v_fmac_f32_e32 v54, v62, v245
	v_fmac_f32_e32 v55, v63, v245
	s_branch .Lrw_ldfin

; template <bool RWKV> __device__ __forceinline__ void scan_chunk(const LAS unsigned char* buf, const LAS unsigned char* img, f32x16 (&T)[2], const ScanSrc& S, int chunk, int w, int lane) {
;     const int r = lane & 31, h = lane >> 5;
;     f32x16 zero;
; #pragma unroll
;     for (int i = 0; i < 16; ++i) zero[i] = 0.f;
;     const bf16x8 vb = *(const LAS bf16x8*)(buf + SB_VT + (32 * w + r) * 48 + 16 * h);
;     f32x16 ry = zero, ry2 = zero;
; #pragma unroll
;     for (int kb = 0; kb < 2; ++kb) {
;         const bf16x8 b0 = pack8r(T[0][8 * kb], T[0][8 * kb + 1], T[0][8 * kb + 2], T[0][8 * kb + 3], T[0][8 * kb + 4], T[0][8 * kb + 5], T[0][8 * kb + 6], T[0][8 * kb + 7]);
;         const bf16x8 b1 = pack8r(T[1][8 * kb], T[1][8 * kb + 1], T[1][8 * kb + 2], T[1][8 * kb + 3], T[1][8 * kb + 4], T[1][8 * kb + 5], T[1][8 * kb + 6], T[1][8 * kb + 7]);
;         ry = MFMA32(lds_aperm(buf + SB_XA + r * 144 + (16 * kb) * 2, h), b0, ry);
;         ry2 = MFMA32(lds_aperm(buf + SB_XA + r * 144 + (32 + 16 * kb) * 2, h), b1, ry2); }
;     { const bf16x8 a = *(const LAS bf16x8*)(img + SW_HT + r * 48 + 16 * h); ry = MFMA32(a, vb, ry); }
; #pragma unroll
;     for (int i = 0; i < 16; ++i) ry[i] += ry2[i];
;     bf16x8 ub;
;     if (RWKV) {
;         const bf16x8 rb = pack8r(ry[0], ry[1], ry[2], ry[3], ry[4], ry[5], ry[6], ry[7]);
;         const f32x16 ua = MFMA32(lds_aperm(img + SW_TIT + r * 48, h), rb, zero);
;         ub = pack8r(ua[0], ua[1], ua[2], ua[3], ua[4], ua[5], ua[6], ua[7]);
;         ry = MFMA32(lds_aperm(img + SW_GYT + r * 48, h), ub, ry);
;     }
;     {
;         const int s0 = chunk * SC_CH; const long tok0 = (long)S.tokbase + (S.rev ? T_SEQ - 1 - s0 : s0), dstep = S.rev ? -512 : 512;
;         bf16_t* op = S.out + tok0 * 512 + 32 * w + r;
; #pragma unroll
;         for (int q = 8; q < 16; ++q) { const int s = (q & 3) + 8 * ((q >> 2) - 2) + 4 * h; op[s * dstep] = (bf16_t)(cvt2(ry[q], 0.f) & 0xffffu); }
;     }
; #pragma unroll
;     for (int jt = 0; jt < 2; ++jt) {
;         if (RWKV) T[jt] = MFMA32(lds_aperm(buf + SB_XBT + (32 * jt + r) * 80, h), ub, T[jt]);
;         { const bf16x8 a = *(const LAS bf16x8*)(buf + SB_XBT + (32 * jt + r) * 80 + 32 + 16 * h); T[jt] = MFMA32(a, vb, T[jt]); }
; #pragma unroll
;         for (int g = 0; g < 4; ++g) { const f32x4 we = *(const LAS f32x4*)(buf + SB_WE + (32 * jt + 8 * g + 4 * h) * 4);
; #pragma unroll
.Lrw_compute:
	s_mul_i32 s0, s70, 0x4500
	s_mul_i32 s1, s72, 0x1600
	v_add3_u32 v242, s0, v135, v136
	v_add_u32_e32 v243, s0, v134
	ds_read2_b64 v[32:35], v242 offset1:2
	ds_read2_b64 v[36:39], v242 offset0:4 offset1:6
	v_add_u32_e32 v245, v243, v152
	ds_read2_b64 v[40:43], v242 offset0:8 offset1:10
	ds_read2_b64 v[44:47], v242 offset0:12 offset1:14
	ds_read_b128 v[48:51], v245 offset:14336
	v_add3_u32 v245, s1, v177, v134
	v_cvt_pk_bf16_f32 v64, v0, v1
	v_cvt_pk_bf16_f32 v65, v2, v3
	v_cvt_pk_bf16_f32 v66, v4, v5
	v_cvt_pk_bf16_f32 v67, v6, v7
	ds_read_b128 v[52:55], v245 offset:1024
	v_add3_u32 v245, s1, v177, v136
	v_add_u32_e32 v242, 0x1000, v245
	ds_read2_b64 v[56:59], v242 offset1:2
	v_add_u32_e32 v242, 0x800, v245
	ds_read2_b64 v[60:63], v242 offset0:64 offset1:66
	v_cvt_pk_bf16_f32 v68, v8, v9
	v_cvt_pk_bf16_f32 v69, v10, v11
	v_cvt_pk_bf16_f32 v70, v12, v13
	v_cvt_pk_bf16_f32 v71, v14, v15
	v_add3_u32 v242, s0, v153, v134
	ds_read_b128 v[250:253], v242 offset:9248
	v_add3_u32 v242, s0, v154, v134
	ds_read_b128 v[118:121], v242 offset:9248
	v_cvt_pk_bf16_f32 v190, v16, v17
	v_cvt_pk_bf16_f32 v191, v18, v19
	v_cvt_pk_bf16_f32 v192, v20, v21
	v_cvt_pk_bf16_f32 v193, v22, v23
	s_waitcnt lgkmcnt(9)
	v_mfma_f32_32x32x16_bf16 v[198:213], v[32:35], v[64:67], 0
	v_cvt_pk_bf16_f32 v194, v24, v25
	v_cvt_pk_bf16_f32 v195, v26, v27
	v_cvt_pk_bf16_f32 v196, v28, v29
	v_cvt_pk_bf16_f32 v197, v30, v31
	v_add3_u32 v242, s0, v153, v136
	v_add_u32_e32 v242, 0x2000, v242
	ds_read2_b64 v[238:241], v242 offset0:128 offset1:130
	v_add3_u32 v242, s0, v154, v136
	v_add_u32_e32 v242, 0x2000, v242
	ds_read2_b64 v[246:249], v242 offset0:128 offset1:130
	s_waitcnt lgkmcnt(10)
	v_mfma_f32_32x32x16_bf16 v[198:213], v[36:39], v[68:71], v[198:213]
	s_waitcnt lgkmcnt(9)
	v_mfma_f32_32x32x16_bf16 v[198:213], v[40:43], v[190:193], v[198:213]
	s_waitcnt lgkmcnt(8)
	v_mfma_f32_32x32x16_bf16 v[198:213], v[44:47], v[194:197], v[198:213]
	s_waitcnt lgkmcnt(6)
	v_mfma_f32_32x32x16_bf16 v[198:213], v[52:55], v[48:51], v[198:213]
	s_waitcnt lgkmcnt(3)
	v_mfma_f32_32x32x16_bf16 v[0:15], v[250:253], v[48:51], v[0:15]
	ds_read_b128 v[32:35], v243 offset:17408
	ds_read_b128 v[36:39], v243 offset:17440
	ds_read_b128 v[40:43], v243 offset:17472
	ds_read_b128 v[44:47], v243 offset:17504
	ds_read_b128 v[64:67], v243 offset:17536
	ds_read_b128 v[68:71], v243 offset:17568
	ds_read_b128 v[190:193], v243 offset:17600
	ds_read_b128 v[194:197], v243 offset:17632
	s_nop 2
	v_cvt_pk_bf16_f32 v214, v198, v199
	v_cvt_pk_bf16_f32 v215, v200, v201
	v_cvt_pk_bf16_f32 v216, v202, v203
	v_cvt_pk_bf16_f32 v217, v204, v205
	s_nop 1
	v_mfma_f32_32x32x16_bf16 v[222:237], v[56:59], v[214:217], 0
	s_waitcnt lgkmcnt(10)
	v_mfma_f32_32x32x16_bf16 v[16:31], v[118:121], v[48:51], v[16:31]
	s_add_i32 s1, s68, 64
	s_and_b64 s[42:43], s[40:41], exec
	s_cselect_b32 s1, s67, s1
	s_add_u32 s42, s1, s83
	s_addc_u32 s43, 0, s66
	s_lshl_b64 s[42:43], s[42:43], 10
	s_add_u32 s42, s42, s98
	s_addc_u32 s43, s43, s99
	s_nop 4
	v_cvt_pk_bf16_f32 v218, v222, v223
	v_cvt_pk_bf16_f32 v219, v224, v225
	v_cvt_pk_bf16_f32 v220, v226, v227
	v_cvt_pk_bf16_f32 v221, v228, v229
	s_nop 1
	v_mfma_f32_32x32x16_bf16 v[198:213], v[60:63], v[218:221], v[198:213]
	s_waitcnt lgkmcnt(9)
	v_mfma_f32_32x32x16_bf16 v[0:15], v[238:241], v[218:221], v[0:15]
	s_waitcnt lgkmcnt(8)
	v_mfma_f32_32x32x16_bf16 v[16:31], v[246:249], v[218:221], v[16:31]
	s_nop 7
	v_cvt_pk_bf16_f32 v218, v206, v207
	v_cvt_pk_bf16_f32 v219, v208, v209
	v_cvt_pk_bf16_f32 v220, v210, v211
	v_cvt_pk_bf16_f32 v221, v212, v213
	global_store_short v102, v218, s[42:43]
	global_store_short_d16_hi v104, v218, s[42:43]
	global_store_short v106, v219, s[42:43]
	global_store_short_d16_hi v108, v219, s[42:43]
	global_store_short v110, v220, s[42:43]
	global_store_short_d16_hi v112, v220, s[42:43]
	global_store_short v114, v221, s[42:43]
	global_store_short_d16_hi v116, v221, s[42:43]
	s_waitcnt lgkmcnt(0)
	v_pk_mul_f32 v[0:1], v[0:1], v[32:33]
	v_pk_mul_f32 v[2:3], v[2:3], v[34:35]
	v_pk_mul_f32 v[4:5], v[4:5], v[36:37]
	v_pk_mul_f32 v[6:7], v[6:7], v[38:39]
	v_pk_mul_f32 v[8:9], v[8:9], v[40:41]
	v_pk_mul_f32 v[10:11], v[10:11], v[42:43]
	v_pk_mul_f32 v[12:13], v[12:13], v[44:45]
	v_pk_mul_f32 v[14:15], v[14:15], v[46:47]
	v_pk_mul_f32 v[16:17], v[16:17], v[64:65]
	v_pk_mul_f32 v[18:19], v[18:19], v[66:67]
	v_pk_mul_f32 v[20:21], v[20:21], v[68:69]
	v_pk_mul_f32 v[22:23], v[22:23], v[70:71]
	v_pk_mul_f32 v[24:25], v[24:25], v[190:191]
	v_pk_mul_f32 v[26:27], v[26:27], v[192:193]
	v_pk_mul_f32 v[28:29], v[28:29], v[194:195]
	v_pk_mul_f32 v[30:31], v[30:31], v[196:197]
	s_branch .LBB0_613
